# v28 + static s_setprio 1 for waves 4-7 during the attention phase
# baseline (speedup 1.0000x reference)
.LBB0_530:
	v_readfirstlane_b32 s99, v184
	s_cmpk_lt_u32 s99, 0x100
	s_cbranch_scc1 .Lattn_prio_done
	s_setprio 1

.LBB0_607:
	s_setprio 0
	s_cmp_gt_i32 s93, 6
	s_cselect_b64 s[0:1], -1, 0
	s_and_b64 s[2:3], s[8:9], s[0:1]
	s_andn2_b64 vcc, exec, s[2:3]
	s_cbranch_vccnz .LBB0_675
	s_cmp_lg_u32 s94, 2
	s_mov_b64 s[2:3], -1
	s_cbranch_scc0 .LBB0_662
	s_waitcnt vmcnt(0)
	s_waitcnt vmcnt(0) lgkmcnt(0)
	s_barrier
	s_mov_b64 s[2:3], exec
	v_readlane_b32 s4, v253, 2
	v_readlane_b32 s5, v253, 3
	s_and_b64 s[4:5], s[2:3], s[4:5]
	s_mov_b64 exec, s[4:5]
	s_cbranch_execz .LBB0_661
	s_add_i32 s4, 0, 0x22000
	v_mov_b32_e32 v1, s4
	s_waitcnt vmcnt(0) expcnt(0) lgkmcnt(0)
	ds_read_b32 v3, v1
	s_add_i32 s4, 0, 0x22004
	v_mov_b32_e32 v1, s4
	ds_read_b32 v1, v1
	s_waitcnt lgkmcnt(1)
	v_cmp_ne_u32_e32 vcc, 0, v3
	s_cbranch_vccnz .LBB0_625
	s_add_u32 s4, s38, 0x1c96c600
	s_addc_u32 s5, s39, 0
	s_add_u32 s8, s38, 0x1c96c800
	s_addc_u32 s9, s39, 0
	s_add_u32 s16, s38, 0x1c96c900
	s_addc_u32 s17, s39, 0
	s_add_u32 s18, s38, 0x1c96ca00
	s_addc_u32 s19, s39, 0
	s_add_u32 s20, s38, 0x1c96cb00
	s_addc_u32 s21, s39, 0
	s_add_u32 s22, s38, 0x1c96cc00
	s_addc_u32 s23, s39, 0
	s_add_u32 s24, s38, 0x1c96cd00
	s_addc_u32 s25, s39, 0
	s_add_u32 s26, s38, 0x1c96ce00
	s_addc_u32 s27, s39, 0
	s_add_u32 s28, s38, 0x1c96cf00
	s_addc_u32 s29, s39, 0
	s_add_u32 s30, s38, 0x1c96d000
	s_addc_u32 s31, s39, 0
	s_add_u32 s34, s38, 0x1c96d100
	s_addc_u32 s35, s39, 0
	s_add_u32 s36, s38, 0x1c96d200
	s_addc_u32 s37, s39, 0
	s_add_u32 s42, s38, 0x1c96d300
	s_addc_u32 s43, s39, 0
	s_add_u32 s44, s38, 0x1c96d400
	s_addc_u32 s45, s39, 0
	s_add_u32 s46, s38, 0x1c96d500
	s_addc_u32 s47, s39, 0
	s_add_u32 s48, s38, 0x1c96d600
	s_addc_u32 s49, s39, 0
	s_mul_i32 s41, s73, s97
	s_add_u32 s50, s38, 0x1c96d700
	s_mul_i32 s41, s41, s72
	s_addc_u32 s51, s39, 0
	s_mov_b32 s52, 1
	v_mov_b32_e32 v17, 0
	s_branch .LBB0_613
